# NSA window loop: the 15 per-tile key-position adds are computed only on tiles that need per-element masks (hazard nop bumped by one to keep the MFMA-to-VALU distance)
# baseline (speedup 1.0000x reference)
.LBB0_644:
	global_load_dwordx4 v[142:145], v[152:153], off
	global_load_dwordx4 v[134:137], v[152:153], off offset:1024
	global_load_dwordx4 v[138:141], v[152:153], off offset:2048
	global_load_dwordx4 v[130:133], v[152:153], off offset:3072
	s_waitcnt vmcnt(4) lgkmcnt(0)
	v_mfma_f32_32x32x16_bf16 v[66:81], v[126:129], v[82:85], 0
	s_add_i32 s6, s8, 31
	s_cmp_gt_i32 s8, s76
	s_cselect_b64 s[4:5], -1, 0
	s_cmp_le_i32 s6, s45
	s_cselect_b64 s[6:7], -1, 0
	s_and_b64 s[6:7], s[4:5], s[6:7]
	v_mfma_f32_32x32x16_bf16 v[66:81], v[122:125], v[86:89], v[66:81]
	s_and_b64 vcc, exec, s[6:7]
	v_mfma_f32_32x32x16_bf16 v[66:81], v[118:121], v[90:93], v[66:81]
	v_mfma_f32_32x32x16_bf16 v[66:81], v[114:117], v[94:97], v[66:81]
	s_cbranch_vccnz .LBB0_646
	v_add_u32_e32 v192, s8, v150
	v_add_u32_e32 v201, 2, v192
	v_add_u32_e32 v200, 3, v192
	v_add_u32_e32 v193, 8, v192
	v_add_u32_e32 v191, 9, v192
	v_add_u32_e32 v190, 10, v192
	v_add_u32_e32 v189, 11, v192
	v_add_u32_e32 v188, 16, v192
	v_add_u32_e32 v187, 17, v192
	v_add_u32_e32 v186, 18, v192
	v_add_u32_e32 v185, 19, v192
	v_add_u32_e32 v184, 24, v192
	v_add_u32_e32 v183, 25, v192
	v_add_u32_e32 v182, 26, v192
	v_add_u32_e32 v181, 27, v192
	v_cmp_le_i32_e32 vcc, v192, v172
	v_cmp_gt_i32_e64 s[4:5], v192, v173
	s_and_b64 vcc, vcc, s[4:5]
	s_nop 6
	v_cndmask_b32_e32 v66, v248, v66, vcc
	v_cmp_lt_i32_e32 vcc, v192, v172
	v_cmp_ge_i32_e64 s[4:5], v192, v173
	s_and_b64 vcc, vcc, s[4:5]
	v_cndmask_b32_e32 v67, v248, v67, vcc
	v_cmp_le_i32_e32 vcc, v201, v172
	v_cmp_gt_i32_e64 s[4:5], v201, v173
	s_and_b64 vcc, vcc, s[4:5]
	v_cndmask_b32_e32 v68, v248, v68, vcc
	v_cmp_le_i32_e32 vcc, v200, v172
	v_cmp_gt_i32_e64 s[4:5], v200, v173
	s_and_b64 vcc, vcc, s[4:5]
	v_cndmask_b32_e32 v69, v248, v69, vcc
	v_cmp_le_i32_e32 vcc, v193, v172
	v_cmp_gt_i32_e64 s[4:5], v193, v173
	s_and_b64 vcc, vcc, s[4:5]
	v_cndmask_b32_e32 v70, v248, v70, vcc
	v_cmp_le_i32_e32 vcc, v191, v172
	v_cmp_gt_i32_e64 s[4:5], v191, v173
	s_and_b64 vcc, vcc, s[4:5]
	v_cndmask_b32_e32 v71, v248, v71, vcc
	v_cmp_le_i32_e32 vcc, v190, v172
	v_cmp_gt_i32_e64 s[4:5], v190, v173
	s_and_b64 vcc, vcc, s[4:5]
	v_cndmask_b32_e32 v72, v248, v72, vcc
	v_cmp_le_i32_e32 vcc, v189, v172
	v_cmp_gt_i32_e64 s[4:5], v189, v173
	s_and_b64 vcc, vcc, s[4:5]
	v_cndmask_b32_e32 v73, v248, v73, vcc
	v_cmp_le_i32_e32 vcc, v188, v172
	v_cmp_gt_i32_e64 s[4:5], v188, v173
	s_and_b64 vcc, vcc, s[4:5]
	v_cndmask_b32_e32 v74, v248, v74, vcc
	v_cmp_le_i32_e32 vcc, v187, v172
	v_cmp_gt_i32_e64 s[4:5], v187, v173
	s_and_b64 vcc, vcc, s[4:5]
	v_cndmask_b32_e32 v75, v248, v75, vcc
	v_cmp_le_i32_e32 vcc, v186, v172
	v_cmp_gt_i32_e64 s[4:5], v186, v173
	s_and_b64 vcc, vcc, s[4:5]
	v_cndmask_b32_e32 v76, v248, v76, vcc
	v_cmp_le_i32_e32 vcc, v185, v172
	v_cmp_gt_i32_e64 s[4:5], v185, v173
	s_and_b64 vcc, vcc, s[4:5]
	v_cndmask_b32_e32 v77, v248, v77, vcc
	v_cmp_le_i32_e32 vcc, v184, v172
	v_cmp_gt_i32_e64 s[4:5], v184, v173
	s_and_b64 vcc, vcc, s[4:5]
	v_cndmask_b32_e32 v78, v248, v78, vcc
	v_cmp_le_i32_e32 vcc, v183, v172
	v_cmp_gt_i32_e64 s[4:5], v183, v173
	s_and_b64 vcc, vcc, s[4:5]
	v_cndmask_b32_e32 v79, v248, v79, vcc
	v_cmp_le_i32_e32 vcc, v182, v172
	v_cmp_gt_i32_e64 s[4:5], v182, v173
	s_and_b64 vcc, vcc, s[4:5]
	v_cndmask_b32_e32 v80, v248, v80, vcc
	v_cmp_le_i32_e32 vcc, v181, v172
	v_cmp_gt_i32_e64 s[4:5], v181, v173
	s_and_b64 vcc, vcc, s[4:5]
	v_cndmask_b32_e32 v81, v248, v81, vcc
.LBB0_646:
	s_nop 10
	v_max_f32_e32 v0, v66, v67
	v_max3_f32 v0, v0, v68, v69
	v_max3_f32 v0, v0, v70, v71
	v_max3_f32 v0, v0, v72, v73
	v_max3_f32 v0, v0, v74, v75
	v_max3_f32 v0, v0, v76, v77
	v_max3_f32 v0, v0, v78, v79
	v_max3_f32 v0, v0, v80, v81
	v_mov_b32_e32 v196, v0
	s_nop 1
	v_permlane32_swap_b32_e32 v0, v196
	v_max_f32_e32 v0, v0, v196
	v_mul_f32_e32 v0, 0x3e38aa3b, v0
	v_max_f32_e32 v0, v202, v0
	v_sub_f32_e32 v196, v0, v202
	v_cmp_lt_f32_e32 vcc, s67, v196
	s_cbranch_vccz .LBB0_648
	v_sub_f32_e32 v196, v202, v0
	v_exp_f32_e32 v202, v196
	s_nop 0
	v_mul_f32_e32 v147, v147, v202
	v_pk_mul_f32 v[64:65], v[64:65], v[202:203] op_sel_hi:[1,0]
	v_pk_mul_f32 v[62:63], v[62:63], v[202:203] op_sel_hi:[1,0]
	v_pk_mul_f32 v[60:61], v[60:61], v[202:203] op_sel_hi:[1,0]
	v_pk_mul_f32 v[58:59], v[58:59], v[202:203] op_sel_hi:[1,0]
	v_pk_mul_f32 v[56:57], v[56:57], v[202:203] op_sel_hi:[1,0]
	v_pk_mul_f32 v[54:55], v[54:55], v[202:203] op_sel_hi:[1,0]
	v_pk_mul_f32 v[52:53], v[52:53], v[202:203] op_sel_hi:[1,0]
	v_pk_mul_f32 v[50:51], v[50:51], v[202:203] op_sel_hi:[1,0]
	v_pk_mul_f32 v[48:49], v[48:49], v[202:203] op_sel_hi:[1,0]
	v_pk_mul_f32 v[46:47], v[46:47], v[202:203] op_sel_hi:[1,0]
	v_pk_mul_f32 v[44:45], v[44:45], v[202:203] op_sel_hi:[1,0]
	v_pk_mul_f32 v[42:43], v[42:43], v[202:203] op_sel_hi:[1,0]
	v_pk_mul_f32 v[40:41], v[40:41], v[202:203] op_sel_hi:[1,0]
	v_pk_mul_f32 v[38:39], v[38:39], v[202:203] op_sel_hi:[1,0]
	v_pk_mul_f32 v[36:37], v[36:37], v[202:203] op_sel_hi:[1,0]
	v_pk_mul_f32 v[34:35], v[34:35], v[202:203] op_sel_hi:[1,0]
	s_branch .LBB0_649
